# v31: v25 + norm phases fully write-through with flat barriers
# speedup vs baseline: 1.0028x; 1.0015x over previous
.LBB0_1347:
	s_cmp_lt_i32 s59, 11
	s_barrier
	s_cbranch_scc1 .LBB0_1401
	s_waitcnt vmcnt(0)
	s_barrier
	s_and_saveexec_b64 s[2:3], s[0:1]
	s_cbranch_execz .LBB0_1400
	s_waitcnt vmcnt(0) lgkmcnt(0)
	v_mov_b32_e32 v241, 0
	v_lshlrev_b32_e64 v254, 8, s31
	v_mov_b32_e32 v247, 1
	v_mov_b32_e32 v246, 0x3600
	global_atomic_add v248, v246, v247, s[60:61] sc0

.LBB0_2462:
	s_cmp_lt_i32 s59, 15
	s_barrier
	s_cbranch_scc1 .LBB0_2516
	s_waitcnt vmcnt(0)
	s_barrier
	s_and_saveexec_b64 s[2:3], s[0:1]
	s_cbranch_execz .LBB0_2515
	s_waitcnt vmcnt(0) lgkmcnt(0)
	v_mov_b32_e32 v241, 0
	v_lshlrev_b32_e64 v254, 8, s31
	v_mov_b32_e32 v247, 1
	v_mov_b32_e32 v246, 0x3600
	global_atomic_add v248, v246, v247, s[60:61] sc0

.LBB0_3217:
	s_cmp_lt_i32 s59, 23
	s_barrier
	s_cbranch_scc1 .LBB0_3271
	s_waitcnt vmcnt(0)
	s_barrier
	s_and_saveexec_b64 s[2:3], s[0:1]
	s_cbranch_execz .LBB0_3270
	s_waitcnt vmcnt(0) lgkmcnt(0)
	v_mov_b32_e32 v241, 0
	v_lshlrev_b32_e64 v254, 8, s31
	v_mov_b32_e32 v247, 1
	v_mov_b32_e32 v246, 0x3600
	global_atomic_add v248, v246, v247, s[60:61] sc0
